# placement pin: the six GEMM K-loop heads aligned to 64 bytes (.p2align 6, nop pad executed once per tile)
# speedup vs baseline: 1.0023x; 1.0023x over previous
;     __device__ bool next(int i, Unit& u) const { if (!b.next(i >> 1, u)) return false; u.half = i & 1; u.koff = (i & 1) * kbytes; return true; }
; template <class Epi, class Sched>
; __device__ __forceinline__ void gemm_phase(LAS unsigned char* lds, const Gemm g, const Sched& S, const Epi& E, int tid_in) {
;     ...
;     for (;;) {
;         const bool has_next = S.next(ui + 1, nxt);
;         const char* nA = has_next ? (const char*)g.A + (size_t)nxt.pm * tstep + nxt.koff : cA; const char* nB = has_next ? (const char*)g.Bt + (size_t)nxt.pn * tstep + nxt.koff : cB;
;         for (int t = 0; t < nt; t += 2) {
;             const bool last = (t == nt - 2);
;             const char* a1 = cA + (size_t)(t + 1) * kstep;
;             const char* a2 = last ? nA : cA + (size_t)(t + 2) * kstep; const char* b2 = last ? nB : cB + (size_t)(t + 2) * kstep;
;             const char* a3 = a2 + kstep; const char* b3 = b2 + kstep;
;     ...
;         if (!keep) {
; #pragma unroll
;             for (int a = 0; a < 2; ++a)
; #pragma unroll
;                 for (int b = 0; b < 2; ++b)
; #pragma unroll
;                     for (int m = 0; m < 4; ++m)
; #pragma unroll
;                         for (int n = 0; n < 2; ++n) acc[a][b][m][n] = (f32x4){0.f, 0.f, 0.f, 0.f};
;         }
;         cur = nxt; cA = nA; cB = nB; ++ui;
.LBB0_101:
	s_ashr_i32 s31, s30, 31
	s_lshl_b64 s[34:35], s[30:31], 20
	s_add_u32 s34, s58, s34
	s_addc_u32 s35, s59, s35
	s_and_b64 s[36:37], s[0:1], exec
	s_cselect_b32 s31, s35, s43
	s_cselect_b32 s39, s34, s42
	s_ashr_i32 s29, s28, 31
	s_lshl_b64 s[36:37], s[28:29], 20
	s_add_u32 s36, s56, s36
	s_addc_u32 s37, s57, s37
	s_and_b64 s[46:47], s[0:1], exec
	s_cselect_b32 s29, s37, s45
	s_cselect_b32 s41, s36, s44
	s_add_u32 s94, s44, 0x100
	v_mov_b32_e32 v0, 0
	s_addc_u32 s95, s45, 0
	s_mov_b32 s96, -2
	s_mov_b64 s[44:45], 0
	v_mov_b32_e32 v1, v0
	v_mov_b32_e32 v2, v0
	v_mov_b32_e32 v3, v0
	v_mov_b32_e32 v4, v0
	v_mov_b32_e32 v5, v0
	v_mov_b32_e32 v6, v0
	v_mov_b32_e32 v7, v0
	v_mov_b32_e32 v16, v0
	v_mov_b32_e32 v17, v0
	v_mov_b32_e32 v18, v0
	v_mov_b32_e32 v19, v0
	v_mov_b32_e32 v20, v0
	v_mov_b32_e32 v21, v0
	v_mov_b32_e32 v22, v0
	v_mov_b32_e32 v23, v0
	v_mov_b32_e32 v32, v0
	v_mov_b32_e32 v33, v0
	v_mov_b32_e32 v34, v0
	v_mov_b32_e32 v35, v0
	v_mov_b32_e32 v36, v0
	v_mov_b32_e32 v37, v0
	v_mov_b32_e32 v38, v0
	v_mov_b32_e32 v39, v0
	v_mov_b32_e32 v48, v0
	v_mov_b32_e32 v49, v0
	v_mov_b32_e32 v50, v0
	v_mov_b32_e32 v51, v0
	v_mov_b32_e32 v52, v0
	v_mov_b32_e32 v53, v0
	v_mov_b32_e32 v54, v0
	v_mov_b32_e32 v55, v0
	v_mov_b32_e32 v8, v0
	v_mov_b32_e32 v9, v0
	v_mov_b32_e32 v10, v0
	v_mov_b32_e32 v11, v0
	v_mov_b32_e32 v12, v0
	v_mov_b32_e32 v13, v0
	v_mov_b32_e32 v14, v0
	v_mov_b32_e32 v15, v0
	v_mov_b32_e32 v24, v0
	v_mov_b32_e32 v25, v0
	v_mov_b32_e32 v26, v0
	v_mov_b32_e32 v27, v0
	v_mov_b32_e32 v28, v0
	v_mov_b32_e32 v29, v0
	v_mov_b32_e32 v30, v0
	v_mov_b32_e32 v31, v0
	v_mov_b32_e32 v40, v0
	v_mov_b32_e32 v41, v0
	v_mov_b32_e32 v42, v0
	v_mov_b32_e32 v43, v0
	v_mov_b32_e32 v44, v0
	v_mov_b32_e32 v45, v0
	v_mov_b32_e32 v46, v0
	v_mov_b32_e32 v47, v0
	v_mov_b32_e32 v56, v0
	v_mov_b32_e32 v57, v0
	v_mov_b32_e32 v58, v0
	v_mov_b32_e32 v59, v0
	v_mov_b32_e32 v60, v0
	v_mov_b32_e32 v61, v0
	v_mov_b32_e32 v62, v0
	v_mov_b32_e32 v63, v0
	v_mov_b32_e32 v64, v0
	v_mov_b32_e32 v65, v0
	v_mov_b32_e32 v66, v0
	v_mov_b32_e32 v67, v0
	v_mov_b32_e32 v68, v0
	v_mov_b32_e32 v69, v0
	v_mov_b32_e32 v70, v0
	v_mov_b32_e32 v71, v0
	v_mov_b32_e32 v80, v0
	v_mov_b32_e32 v81, v0
	v_mov_b32_e32 v82, v0
	v_mov_b32_e32 v83, v0
	v_mov_b32_e32 v84, v0
	v_mov_b32_e32 v85, v0
	v_mov_b32_e32 v86, v0
	v_mov_b32_e32 v87, v0
	v_mov_b32_e32 v96, v0
	v_mov_b32_e32 v97, v0
	v_mov_b32_e32 v98, v0
	v_mov_b32_e32 v99, v0
	v_mov_b32_e32 v100, v0
	v_mov_b32_e32 v101, v0
	v_mov_b32_e32 v102, v0
	v_mov_b32_e32 v103, v0
	v_mov_b32_e32 v112, v0
	v_mov_b32_e32 v113, v0
	v_mov_b32_e32 v114, v0
	v_mov_b32_e32 v115, v0
	v_mov_b32_e32 v116, v0
	v_mov_b32_e32 v117, v0
	v_mov_b32_e32 v118, v0
	v_mov_b32_e32 v119, v0
	v_mov_b32_e32 v72, v0
	v_mov_b32_e32 v73, v0
	v_mov_b32_e32 v74, v0
	v_mov_b32_e32 v75, v0
	v_mov_b32_e32 v76, v0
	v_mov_b32_e32 v77, v0
	v_mov_b32_e32 v78, v0
	v_mov_b32_e32 v79, v0
	v_mov_b32_e32 v88, v0
	v_mov_b32_e32 v89, v0
	v_mov_b32_e32 v90, v0
	v_mov_b32_e32 v91, v0
	v_mov_b32_e32 v92, v0
	v_mov_b32_e32 v93, v0
	v_mov_b32_e32 v94, v0
	v_mov_b32_e32 v95, v0
	v_mov_b32_e32 v104, v0
	v_mov_b32_e32 v105, v0
	v_mov_b32_e32 v106, v0
	v_mov_b32_e32 v107, v0
	v_mov_b32_e32 v108, v0
	v_mov_b32_e32 v109, v0
	v_mov_b32_e32 v110, v0
	v_mov_b32_e32 v111, v0
	v_mov_b32_e32 v120, v0
	v_mov_b32_e32 v121, v0
	v_mov_b32_e32 v122, v0
	v_mov_b32_e32 v123, v0
	v_mov_b32_e32 v124, v0
	v_mov_b32_e32 v125, v0
	v_mov_b32_e32 v126, v0
	v_mov_b32_e32 v127, v0
	v_lshl_add_u64 v[128:129], s[42:43], 0, v[158:159]
	v_lshl_add_u64 v[130:131], s[42:43], 0, v[160:161]
	.p2align 6

;     __device__ bool next(int i, Unit& u) const { if (!b.next(i >> 1, u)) return false; u.half = i & 1; u.koff = (i & 1) * kbytes; return true; }
; template <class Epi, class Sched>
; __device__ __forceinline__ void gemm_phase(LAS unsigned char* lds, const Gemm g, const Sched& S, const Epi& E, int tid_in) {
;     ...
;         const bool has_next = S.next(ui + 1, nxt);
;         const char* nA = has_next ? (const char*)g.A + (size_t)nxt.pm * tstep + nxt.koff : cA; const char* nB = has_next ? (const char*)g.Bt + (size_t)nxt.pn * tstep + nxt.koff : cB;
;         for (int t = 0; t < nt; t += 2) {
;             const bool last = (t == nt - 2);
;             const char* a1 = cA + (size_t)(t + 1) * kstep;
;             const char* a2 = last ? nA : cA + (size_t)(t + 2) * kstep; const char* b2 = last ? nB : cB + (size_t)(t + 2) * kstep;
;             const char* a3 = a2 + kstep; const char* b3 = b2 + kstep;
.LBB0_510:
	s_ashr_i32 s29, s28, 31
	s_lshl_b64 s[30:31], s[28:29], 20
	s_add_u32 s27, s58, s30
	s_addc_u32 s29, s59, s31
	s_ashr_i32 s42, s75, 31
	s_add_u32 s30, s27, s75
	s_addc_u32 s31, s29, s42
	s_and_b64 s[34:35], s[6:7], exec
	s_cselect_b32 s29, s31, s39
	s_cselect_b32 s37, s30, s38
	s_ashr_i32 s27, s26, 31
	s_lshl_b64 s[34:35], s[26:27], 20
	s_add_u32 s27, s70, s34
	s_addc_u32 s35, s71, s35
	s_add_u32 s34, s27, s75
	s_addc_u32 s35, s35, s42
	s_and_b64 s[42:43], s[6:7], exec
	s_cselect_b32 s27, s35, s41
	s_cselect_b32 s76, s34, s40
	s_add_u32 s77, s40, 0x100
	v_lshl_add_u64 v[128:129], s[38:39], 0, v[164:165]
	v_lshl_add_u64 v[130:131], s[38:39], 0, v[166:167]
	s_addc_u32 s78, s41, 0
	s_mov_b32 s79, -2
	s_mov_b64 s[40:41], 0
	.p2align 6

;     __device__ bool next(int i, Unit& u) const { if (!b.next(i >> 1, u)) return false; u.half = i & 1; u.koff = (i & 1) * kbytes; return true; }
; template <class Epi, class Sched>
; __device__ __forceinline__ void gemm_phase(LAS unsigned char* lds, const Gemm g, const Sched& S, const Epi& E, int tid_in) {
;     ...
;     for (;;) {
;         const bool has_next = S.next(ui + 1, nxt);
;         const char* nA = has_next ? (const char*)g.A + (size_t)nxt.pm * tstep + nxt.koff : cA; const char* nB = has_next ? (const char*)g.Bt + (size_t)nxt.pn * tstep + nxt.koff : cB;
;         for (int t = 0; t < nt; t += 2) {
;             const bool last = (t == nt - 2);
;             const char* a1 = cA + (size_t)(t + 1) * kstep;
;             const char* a2 = last ? nA : cA + (size_t)(t + 2) * kstep; const char* b2 = last ? nB : cB + (size_t)(t + 2) * kstep;
;             const char* a3 = a2 + kstep; const char* b3 = b2 + kstep;
;     ...
;         if (!keep) {
; #pragma unroll
;             for (int a = 0; a < 2; ++a)
; #pragma unroll
;                 for (int b = 0; b < 2; ++b)
; #pragma unroll
;                     for (int m = 0; m < 4; ++m)
; #pragma unroll
;                         for (int n = 0; n < 2; ++n) acc[a][b][m][n] = (f32x4){0.f, 0.f, 0.f, 0.f};
;         }
;         cur = nxt; cA = nA; cB = nB; ++ui;
.LBB0_619:
	s_ashr_i32 s25, s24, 31
	s_lshl_b64 s[26:27], s[24:25], 20
	s_add_u32 s26, s8, s26
	s_addc_u32 s27, s9, s27
	s_and_b64 s[28:29], s[4:5], exec
	s_cselect_b32 s25, s27, s35
	s_cselect_b32 s31, s26, s34
	s_ashr_i32 s23, s22, 31
	s_lshl_b64 s[28:29], s[22:23], 20
	s_add_u32 s28, s68, s28
	s_addc_u32 s29, s69, s29
	s_and_b64 s[38:39], s[4:5], exec
	s_cselect_b32 s23, s29, s37
	s_cselect_b32 s49, s28, s36
	s_add_u32 s51, s36, 0x100
	v_mov_b32_e32 v0, 0
	s_addc_u32 s70, s37, 0
	v_lshl_add_u64 v[144:145], s[34:35], 0, v[136:137]
	v_lshl_add_u64 v[146:147], s[34:35], 0, v[138:139]
	s_mov_b32 s71, -2
	s_mov_b64 s[36:37], 0
	v_mov_b32_e32 v1, v0
	v_mov_b32_e32 v2, v0
	v_mov_b32_e32 v3, v0
	v_mov_b32_e32 v4, v0
	s_waitcnt lgkmcnt(0)
	v_mov_b32_e32 v5, v0
	v_mov_b32_e32 v6, v0
	v_mov_b32_e32 v7, v0
	v_mov_b32_e32 v16, v0
	v_mov_b32_e32 v17, v0
	v_mov_b32_e32 v18, v0
	v_mov_b32_e32 v19, v0
	v_mov_b32_e32 v20, v0
	v_mov_b32_e32 v21, v0
	v_mov_b32_e32 v22, v0
	v_mov_b32_e32 v23, v0
	v_mov_b32_e32 v32, v0
	v_mov_b32_e32 v33, v0
	v_mov_b32_e32 v34, v0
	v_mov_b32_e32 v35, v0
	v_mov_b32_e32 v36, v0
	v_mov_b32_e32 v37, v0
	v_mov_b32_e32 v38, v0
	v_mov_b32_e32 v39, v0
	v_mov_b32_e32 v48, v0
	v_mov_b32_e32 v49, v0
	v_mov_b32_e32 v50, v0
	v_mov_b32_e32 v51, v0
	v_mov_b32_e32 v52, v0
	v_mov_b32_e32 v53, v0
	v_mov_b32_e32 v54, v0
	v_mov_b32_e32 v55, v0
	v_mov_b32_e32 v8, v0
	v_mov_b32_e32 v9, v0
	v_mov_b32_e32 v10, v0
	v_mov_b32_e32 v11, v0
	v_mov_b32_e32 v12, v0
	v_mov_b32_e32 v13, v0
	v_mov_b32_e32 v14, v0
	v_mov_b32_e32 v15, v0
	v_mov_b32_e32 v24, v0
	v_mov_b32_e32 v25, v0
	v_mov_b32_e32 v26, v0
	v_mov_b32_e32 v27, v0
	v_mov_b32_e32 v28, v0
	v_mov_b32_e32 v29, v0
	v_mov_b32_e32 v30, v0
	v_mov_b32_e32 v31, v0
	v_mov_b32_e32 v40, v0
	v_mov_b32_e32 v41, v0
	v_mov_b32_e32 v42, v0
	v_mov_b32_e32 v43, v0
	v_mov_b32_e32 v44, v0
	v_mov_b32_e32 v45, v0
	v_mov_b32_e32 v46, v0
	v_mov_b32_e32 v47, v0
	v_mov_b32_e32 v56, v0
	v_mov_b32_e32 v57, v0
	v_mov_b32_e32 v58, v0
	v_mov_b32_e32 v59, v0
	v_mov_b32_e32 v60, v0
	v_mov_b32_e32 v61, v0
	v_mov_b32_e32 v62, v0
	v_mov_b32_e32 v63, v0
	v_mov_b32_e32 v64, v0
	v_mov_b32_e32 v65, v0
	v_mov_b32_e32 v66, v0
	v_mov_b32_e32 v67, v0
	v_mov_b32_e32 v68, v0
	v_mov_b32_e32 v69, v0
	v_mov_b32_e32 v70, v0
	v_mov_b32_e32 v71, v0
	v_mov_b32_e32 v80, v0
	v_mov_b32_e32 v81, v0
	v_mov_b32_e32 v82, v0
	v_mov_b32_e32 v83, v0
	v_mov_b32_e32 v84, v0
	v_mov_b32_e32 v85, v0
	v_mov_b32_e32 v86, v0
	v_mov_b32_e32 v87, v0
	v_mov_b32_e32 v96, v0
	v_mov_b32_e32 v97, v0
	v_mov_b32_e32 v98, v0
	v_mov_b32_e32 v99, v0
	v_mov_b32_e32 v100, v0
	v_mov_b32_e32 v101, v0
	v_mov_b32_e32 v102, v0
	v_mov_b32_e32 v103, v0
	v_mov_b32_e32 v112, v0
	v_mov_b32_e32 v113, v0
	v_mov_b32_e32 v114, v0
	v_mov_b32_e32 v115, v0
	v_mov_b32_e32 v116, v0
	v_mov_b32_e32 v117, v0
	v_mov_b32_e32 v118, v0
	v_mov_b32_e32 v119, v0
	v_mov_b32_e32 v72, v0
	v_mov_b32_e32 v73, v0
	v_mov_b32_e32 v74, v0
	v_mov_b32_e32 v75, v0
	v_mov_b32_e32 v76, v0
	v_mov_b32_e32 v77, v0
	v_mov_b32_e32 v78, v0
	v_mov_b32_e32 v79, v0
	v_mov_b32_e32 v88, v0
	v_mov_b32_e32 v89, v0
	v_mov_b32_e32 v90, v0
	v_mov_b32_e32 v91, v0
	v_mov_b32_e32 v92, v0
	v_mov_b32_e32 v93, v0
	v_mov_b32_e32 v94, v0
	v_mov_b32_e32 v95, v0
	v_mov_b32_e32 v104, v0
	v_mov_b32_e32 v105, v0
	v_mov_b32_e32 v106, v0
	v_mov_b32_e32 v107, v0
	v_mov_b32_e32 v108, v0
	v_mov_b32_e32 v109, v0
	v_mov_b32_e32 v110, v0
	v_mov_b32_e32 v111, v0
	v_mov_b32_e32 v120, v0
	v_mov_b32_e32 v121, v0
	v_mov_b32_e32 v122, v0
	v_mov_b32_e32 v123, v0
	v_mov_b32_e32 v124, v0
	v_mov_b32_e32 v125, v0
	v_mov_b32_e32 v126, v0
	v_mov_b32_e32 v127, v0
	.p2align 6

;     __device__ bool next(int i, Unit& u) const { if (!b.next(i >> 1, u)) return false; u.half = i & 1; u.koff = (i & 1) * kbytes; return true; }
; template <class Epi, class Sched>
; __device__ __forceinline__ void gemm_phase(LAS unsigned char* lds, const Gemm g, const Sched& S, const Epi& E, int tid_in) {
;     ...
;     for (;;) {
;         const bool has_next = S.next(ui + 1, nxt);
;         const char* nA = has_next ? (const char*)g.A + (size_t)nxt.pm * tstep + nxt.koff : cA; const char* nB = has_next ? (const char*)g.Bt + (size_t)nxt.pn * tstep + nxt.koff : cB;
;         for (int t = 0; t < nt; t += 2) {
;             const bool last = (t == nt - 2);
;             const char* a1 = cA + (size_t)(t + 1) * kstep;
;             const char* a2 = last ? nA : cA + (size_t)(t + 2) * kstep; const char* b2 = last ? nB : cB + (size_t)(t + 2) * kstep;
;             const char* a3 = a2 + kstep; const char* b3 = b2 + kstep;
;     ...
;         if (!keep) {
; #pragma unroll
;             for (int a = 0; a < 2; ++a)
; #pragma unroll
;                 for (int b = 0; b < 2; ++b)
; #pragma unroll
;                     for (int m = 0; m < 4; ++m)
; #pragma unroll
;                         for (int n = 0; n < 2; ++n) acc[a][b][m][n] = (f32x4){0.f, 0.f, 0.f, 0.f};
;         }
;         cur = nxt; cA = nA; cB = nB; ++ui;
.LBB0_762:
	s_ashr_i32 s21, s20, 31
	s_lshl_b64 s[22:23], s[20:21], 20
	s_add_u32 s22, s58, s22
	s_addc_u32 s23, s59, s23
	s_and_b64 s[24:25], s[4:5], exec
	s_cselect_b32 s21, s23, s29
	s_cselect_b32 s48, s22, s28
	s_ashr_i32 s19, s18, 31
	s_lshl_b64 s[24:25], s[18:19], 20
	s_add_u32 s24, s2, s24
	s_addc_u32 s25, s3, s25
	s_and_b64 s[34:35], s[4:5], exec
	s_cselect_b32 s19, s25, s31
	s_cselect_b32 s49, s24, s30
	s_add_u32 s51, s30, 0x100
	v_mov_b32_e32 v0, 0
	v_lshl_add_u64 v[144:145], s[28:29], 0, v[136:137]
	v_lshl_add_u64 v[146:147], s[28:29], 0, v[138:139]
	s_addc_u32 s68, s31, 0
	s_mov_b32 s69, -2
	s_mov_b64 s[30:31], 0
	v_mov_b32_e32 v1, v0
	v_mov_b32_e32 v2, v0
	v_mov_b32_e32 v3, v0
	v_mov_b32_e32 v4, v0
	v_mov_b32_e32 v5, v0
	v_mov_b32_e32 v6, v0
	v_mov_b32_e32 v7, v0
	v_mov_b32_e32 v16, v0
	v_mov_b32_e32 v17, v0
	v_mov_b32_e32 v18, v0
	v_mov_b32_e32 v19, v0
	v_mov_b32_e32 v20, v0
	v_mov_b32_e32 v21, v0
	v_mov_b32_e32 v22, v0
	v_mov_b32_e32 v23, v0
	v_mov_b32_e32 v32, v0
	v_mov_b32_e32 v33, v0
	v_mov_b32_e32 v34, v0
	v_mov_b32_e32 v35, v0
	v_mov_b32_e32 v36, v0
	v_mov_b32_e32 v37, v0
	v_mov_b32_e32 v38, v0
	v_mov_b32_e32 v39, v0
	v_mov_b32_e32 v48, v0
	v_mov_b32_e32 v49, v0
	v_mov_b32_e32 v50, v0
	v_mov_b32_e32 v51, v0
	v_mov_b32_e32 v52, v0
	v_mov_b32_e32 v53, v0
	v_mov_b32_e32 v54, v0
	v_mov_b32_e32 v55, v0
	v_mov_b32_e32 v8, v0
	v_mov_b32_e32 v9, v0
	v_mov_b32_e32 v10, v0
	v_mov_b32_e32 v11, v0
	v_mov_b32_e32 v12, v0
	v_mov_b32_e32 v13, v0
	v_mov_b32_e32 v14, v0
	v_mov_b32_e32 v15, v0
	v_mov_b32_e32 v24, v0
	v_mov_b32_e32 v25, v0
	v_mov_b32_e32 v26, v0
	v_mov_b32_e32 v27, v0
	v_mov_b32_e32 v28, v0
	v_mov_b32_e32 v29, v0
	v_mov_b32_e32 v30, v0
	v_mov_b32_e32 v31, v0
	v_mov_b32_e32 v40, v0
	v_mov_b32_e32 v41, v0
	v_mov_b32_e32 v42, v0
	v_mov_b32_e32 v43, v0
	v_mov_b32_e32 v44, v0
	v_mov_b32_e32 v45, v0
	v_mov_b32_e32 v46, v0
	v_mov_b32_e32 v47, v0
	v_mov_b32_e32 v56, v0
	v_mov_b32_e32 v57, v0
	v_mov_b32_e32 v58, v0
	v_mov_b32_e32 v59, v0
	v_mov_b32_e32 v60, v0
	v_mov_b32_e32 v61, v0
	v_mov_b32_e32 v62, v0
	v_mov_b32_e32 v63, v0
	v_mov_b32_e32 v64, v0
	v_mov_b32_e32 v65, v0
	v_mov_b32_e32 v66, v0
	v_mov_b32_e32 v67, v0
	v_mov_b32_e32 v68, v0
	v_mov_b32_e32 v69, v0
	v_mov_b32_e32 v70, v0
	v_mov_b32_e32 v71, v0
	v_mov_b32_e32 v80, v0
	v_mov_b32_e32 v81, v0
	v_mov_b32_e32 v82, v0
	v_mov_b32_e32 v83, v0
	v_mov_b32_e32 v84, v0
	v_mov_b32_e32 v85, v0
	v_mov_b32_e32 v86, v0
	v_mov_b32_e32 v87, v0
	v_mov_b32_e32 v96, v0
	v_mov_b32_e32 v97, v0
	v_mov_b32_e32 v98, v0
	v_mov_b32_e32 v99, v0
	v_mov_b32_e32 v100, v0
	v_mov_b32_e32 v101, v0
	v_mov_b32_e32 v102, v0
	v_mov_b32_e32 v103, v0
	v_mov_b32_e32 v112, v0
	v_mov_b32_e32 v113, v0
	v_mov_b32_e32 v114, v0
	v_mov_b32_e32 v115, v0
	v_mov_b32_e32 v116, v0
	v_mov_b32_e32 v117, v0
	v_mov_b32_e32 v118, v0
	v_mov_b32_e32 v119, v0
	v_mov_b32_e32 v72, v0
	v_mov_b32_e32 v73, v0
	v_mov_b32_e32 v74, v0
	v_mov_b32_e32 v75, v0
	v_mov_b32_e32 v76, v0
	v_mov_b32_e32 v77, v0
	v_mov_b32_e32 v78, v0
	v_mov_b32_e32 v79, v0
	v_mov_b32_e32 v88, v0
	v_mov_b32_e32 v89, v0
	v_mov_b32_e32 v90, v0
	v_mov_b32_e32 v91, v0
	v_mov_b32_e32 v92, v0
	v_mov_b32_e32 v93, v0
	v_mov_b32_e32 v94, v0
	v_mov_b32_e32 v95, v0
	v_mov_b32_e32 v104, v0
	v_mov_b32_e32 v105, v0
	v_mov_b32_e32 v106, v0
	v_mov_b32_e32 v107, v0
	v_mov_b32_e32 v108, v0
	v_mov_b32_e32 v109, v0
	v_mov_b32_e32 v110, v0
	v_mov_b32_e32 v111, v0
	v_mov_b32_e32 v120, v0
	v_mov_b32_e32 v121, v0
	v_mov_b32_e32 v122, v0
	v_mov_b32_e32 v123, v0
	v_mov_b32_e32 v124, v0
	v_mov_b32_e32 v125, v0
	v_mov_b32_e32 v126, v0
	v_mov_b32_e32 v127, v0
	.p2align 6

;     __device__ bool next(int i, Unit& u) const { if (!b.next(i >> 1, u)) return false; u.half = i & 1; u.koff = (i & 1) * kbytes; return true; }
; template <class Epi, class Sched>
; __device__ __forceinline__ void gemm_phase(LAS unsigned char* lds, const Gemm g, const Sched& S, const Epi& E, int tid_in) {
;     ...
;     for (;;) {
;         const bool has_next = S.next(ui + 1, nxt);
;         const char* nA = has_next ? (const char*)g.A + (size_t)nxt.pm * tstep + nxt.koff : cA; const char* nB = has_next ? (const char*)g.Bt + (size_t)nxt.pn * tstep + nxt.koff : cB;
;         for (int t = 0; t < nt; t += 2) {
;             const bool last = (t == nt - 2);
;             const char* a1 = cA + (size_t)(t + 1) * kstep;
;             const char* a2 = last ? nA : cA + (size_t)(t + 2) * kstep; const char* b2 = last ? nB : cB + (size_t)(t + 2) * kstep;
;             const char* a3 = a2 + kstep; const char* b3 = b2 + kstep;
;     ...
;         if (!keep) {
; #pragma unroll
;             for (int a = 0; a < 2; ++a)
; #pragma unroll
;                 for (int b = 0; b < 2; ++b)
; #pragma unroll
;                     for (int m = 0; m < 4; ++m)
; #pragma unroll
;                         for (int n = 0; n < 2; ++n) acc[a][b][m][n] = (f32x4){0.f, 0.f, 0.f, 0.f};
;         }
;         cur = nxt; cA = nA; cB = nB; ++ui;
.LBB0_841:
	s_add_u32 s46, s28, 0x100
	v_mov_b32_e32 v0, 0
	s_addc_u32 s47, s29, 0
	v_lshl_add_u64 v[144:145], s[26:27], 0, v[136:137]
	v_lshl_add_u64 v[146:147], s[26:27], 0, v[138:139]
	s_mov_b32 s48, -2
	s_mov_b64 s[28:29], 0
	v_mov_b32_e32 v1, v0
	v_mov_b32_e32 v2, v0
	v_mov_b32_e32 v3, v0
	v_mov_b32_e32 v4, v0
	s_waitcnt lgkmcnt(0)
	v_mov_b32_e32 v5, v0
	v_mov_b32_e32 v6, v0
	v_mov_b32_e32 v7, v0
	v_mov_b32_e32 v16, v0
	v_mov_b32_e32 v17, v0
	v_mov_b32_e32 v18, v0
	v_mov_b32_e32 v19, v0
	v_mov_b32_e32 v20, v0
	v_mov_b32_e32 v21, v0
	v_mov_b32_e32 v22, v0
	v_mov_b32_e32 v23, v0
	v_mov_b32_e32 v32, v0
	v_mov_b32_e32 v33, v0
	v_mov_b32_e32 v34, v0
	v_mov_b32_e32 v35, v0
	v_mov_b32_e32 v36, v0
	v_mov_b32_e32 v37, v0
	v_mov_b32_e32 v38, v0
	v_mov_b32_e32 v39, v0
	v_mov_b32_e32 v48, v0
	v_mov_b32_e32 v49, v0
	v_mov_b32_e32 v50, v0
	v_mov_b32_e32 v51, v0
	v_mov_b32_e32 v52, v0
	v_mov_b32_e32 v53, v0
	v_mov_b32_e32 v54, v0
	v_mov_b32_e32 v55, v0
	v_mov_b32_e32 v8, v0
	v_mov_b32_e32 v9, v0
	v_mov_b32_e32 v10, v0
	v_mov_b32_e32 v11, v0
	v_mov_b32_e32 v12, v0
	v_mov_b32_e32 v13, v0
	v_mov_b32_e32 v14, v0
	v_mov_b32_e32 v15, v0
	v_mov_b32_e32 v24, v0
	v_mov_b32_e32 v25, v0
	v_mov_b32_e32 v26, v0
	v_mov_b32_e32 v27, v0
	v_mov_b32_e32 v28, v0
	v_mov_b32_e32 v29, v0
	v_mov_b32_e32 v30, v0
	v_mov_b32_e32 v31, v0
	v_mov_b32_e32 v40, v0
	v_mov_b32_e32 v41, v0
	v_mov_b32_e32 v42, v0
	v_mov_b32_e32 v43, v0
	v_mov_b32_e32 v44, v0
	v_mov_b32_e32 v45, v0
	v_mov_b32_e32 v46, v0
	v_mov_b32_e32 v47, v0
	v_mov_b32_e32 v56, v0
	v_mov_b32_e32 v57, v0
	v_mov_b32_e32 v58, v0
	v_mov_b32_e32 v59, v0
	v_mov_b32_e32 v60, v0
	v_mov_b32_e32 v61, v0
	v_mov_b32_e32 v62, v0
	v_mov_b32_e32 v63, v0
	v_mov_b32_e32 v64, v0
	v_mov_b32_e32 v65, v0
	v_mov_b32_e32 v66, v0
	v_mov_b32_e32 v67, v0
	v_mov_b32_e32 v68, v0
	v_mov_b32_e32 v69, v0
	v_mov_b32_e32 v70, v0
	v_mov_b32_e32 v71, v0
	v_mov_b32_e32 v80, v0
	v_mov_b32_e32 v81, v0
	v_mov_b32_e32 v82, v0
	v_mov_b32_e32 v83, v0
	v_mov_b32_e32 v84, v0
	v_mov_b32_e32 v85, v0
	v_mov_b32_e32 v86, v0
	v_mov_b32_e32 v87, v0
	v_mov_b32_e32 v96, v0
	v_mov_b32_e32 v97, v0
	v_mov_b32_e32 v98, v0
	v_mov_b32_e32 v99, v0
	v_mov_b32_e32 v100, v0
	v_mov_b32_e32 v101, v0
	v_mov_b32_e32 v102, v0
	v_mov_b32_e32 v103, v0
	v_mov_b32_e32 v112, v0
	v_mov_b32_e32 v113, v0
	v_mov_b32_e32 v114, v0
	v_mov_b32_e32 v115, v0
	v_mov_b32_e32 v116, v0
	v_mov_b32_e32 v117, v0
	v_mov_b32_e32 v118, v0
	v_mov_b32_e32 v119, v0
	v_mov_b32_e32 v72, v0
	v_mov_b32_e32 v73, v0
	v_mov_b32_e32 v74, v0
	v_mov_b32_e32 v75, v0
	v_mov_b32_e32 v76, v0
	v_mov_b32_e32 v77, v0
	v_mov_b32_e32 v78, v0
	v_mov_b32_e32 v79, v0
	v_mov_b32_e32 v88, v0
	v_mov_b32_e32 v89, v0
	v_mov_b32_e32 v90, v0
	v_mov_b32_e32 v91, v0
	v_mov_b32_e32 v92, v0
	v_mov_b32_e32 v93, v0
	v_mov_b32_e32 v94, v0
	v_mov_b32_e32 v95, v0
	v_mov_b32_e32 v104, v0
	v_mov_b32_e32 v105, v0
	v_mov_b32_e32 v106, v0
	v_mov_b32_e32 v107, v0
	v_mov_b32_e32 v108, v0
	v_mov_b32_e32 v109, v0
	v_mov_b32_e32 v110, v0
	v_mov_b32_e32 v111, v0
	v_mov_b32_e32 v120, v0
	v_mov_b32_e32 v121, v0
	v_mov_b32_e32 v122, v0
	v_mov_b32_e32 v123, v0
	v_mov_b32_e32 v124, v0
	v_mov_b32_e32 v125, v0
	v_mov_b32_e32 v126, v0
	v_mov_b32_e32 v127, v0
	.p2align 6

;     __device__ bool next(int i, Unit& u) const { if (!b.next(i >> 1, u)) return false; u.half = i & 1; u.koff = (i & 1) * kbytes; return true; }
; template <class Epi, class Sched>
; __device__ __forceinline__ void gemm_phase(LAS unsigned char* lds, const Gemm g, const Sched& S, const Epi& E, int tid_in) {
;     ...
;     for (;;) {
;         const bool has_next = S.next(ui + 1, nxt);
;         const char* nA = has_next ? (const char*)g.A + (size_t)nxt.pm * tstep + nxt.koff : cA; const char* nB = has_next ? (const char*)g.Bt + (size_t)nxt.pn * tstep + nxt.koff : cB;
;         for (int t = 0; t < nt; t += 2) {
;             const bool last = (t == nt - 2);
;             const char* a1 = cA + (size_t)(t + 1) * kstep;
;             const char* a2 = last ? nA : cA + (size_t)(t + 2) * kstep; const char* b2 = last ? nB : cB + (size_t)(t + 2) * kstep;
;             const char* a3 = a2 + kstep; const char* b3 = b2 + kstep;
;     ...
;         if (!keep) {
; #pragma unroll
;             for (int a = 0; a < 2; ++a)
; #pragma unroll
;                 for (int b = 0; b < 2; ++b)
; #pragma unroll
;                     for (int m = 0; m < 4; ++m)
; #pragma unroll
;                         for (int n = 0; n < 2; ++n) acc[a][b][m][n] = (f32x4){0.f, 0.f, 0.f, 0.f};
;         }
;         cur = nxt; cA = nA; cB = nB; ++ui;
.LBB0_1008:
	s_ashr_i32 s23, s22, 31
	s_lshl_b64 s[24:25], s[22:23], 20
	s_add_u32 s24, s58, s24
	s_addc_u32 s25, s59, s25
	s_and_b64 s[26:27], s[4:5], exec
	s_cselect_b32 s23, s25, s31
	s_cselect_b32 s29, s24, s30
	s_ashr_i32 s21, s20, 31
	s_lshl_b64 s[26:27], s[20:21], 20
	s_add_u32 s26, s60, s26
	s_addc_u32 s27, s61, s27
	s_and_b64 s[36:37], s[4:5], exec
	s_cselect_b32 s21, s27, s35
	s_cselect_b32 s47, s26, s34
	s_add_u32 s48, s34, 0x100
	v_mov_b32_e32 v0, 0
	v_lshl_add_u64 v[144:145], s[30:31], 0, v[136:137]
	v_lshl_add_u64 v[146:147], s[30:31], 0, v[138:139]
	s_addc_u32 s49, s35, 0
	s_mov_b32 s51, -2
	s_mov_b64 s[34:35], 0
	s_waitcnt lgkmcnt(0)
	v_mov_b32_e32 v1, v0
	v_mov_b32_e32 v2, v0
	v_mov_b32_e32 v3, v0
	v_mov_b32_e32 v4, v0
	v_mov_b32_e32 v5, v0
	v_mov_b32_e32 v6, v0
	v_mov_b32_e32 v7, v0
	v_mov_b32_e32 v16, v0
	v_mov_b32_e32 v17, v0
	v_mov_b32_e32 v18, v0
	v_mov_b32_e32 v19, v0
	v_mov_b32_e32 v20, v0
	v_mov_b32_e32 v21, v0
	v_mov_b32_e32 v22, v0
	v_mov_b32_e32 v23, v0
	v_mov_b32_e32 v32, v0
	v_mov_b32_e32 v33, v0
	v_mov_b32_e32 v34, v0
	v_mov_b32_e32 v35, v0
	v_mov_b32_e32 v36, v0
	v_mov_b32_e32 v37, v0
	v_mov_b32_e32 v38, v0
	v_mov_b32_e32 v39, v0
	v_mov_b32_e32 v48, v0
	v_mov_b32_e32 v49, v0
	v_mov_b32_e32 v50, v0
	v_mov_b32_e32 v51, v0
	v_mov_b32_e32 v52, v0
	v_mov_b32_e32 v53, v0
	v_mov_b32_e32 v54, v0
	v_mov_b32_e32 v55, v0
	v_mov_b32_e32 v8, v0
	v_mov_b32_e32 v9, v0
	v_mov_b32_e32 v10, v0
	v_mov_b32_e32 v11, v0
	v_mov_b32_e32 v12, v0
	v_mov_b32_e32 v13, v0
	v_mov_b32_e32 v14, v0
	v_mov_b32_e32 v15, v0
	v_mov_b32_e32 v24, v0
	v_mov_b32_e32 v25, v0
	v_mov_b32_e32 v26, v0
	v_mov_b32_e32 v27, v0
	v_mov_b32_e32 v28, v0
	v_mov_b32_e32 v29, v0
	v_mov_b32_e32 v30, v0
	v_mov_b32_e32 v31, v0
	v_mov_b32_e32 v40, v0
	v_mov_b32_e32 v41, v0
	v_mov_b32_e32 v42, v0
	v_mov_b32_e32 v43, v0
	v_mov_b32_e32 v44, v0
	v_mov_b32_e32 v45, v0
	v_mov_b32_e32 v46, v0
	v_mov_b32_e32 v47, v0
	v_mov_b32_e32 v56, v0
	v_mov_b32_e32 v57, v0
	v_mov_b32_e32 v58, v0
	v_mov_b32_e32 v59, v0
	v_mov_b32_e32 v60, v0
	v_mov_b32_e32 v61, v0
	v_mov_b32_e32 v62, v0
	v_mov_b32_e32 v63, v0
	v_mov_b32_e32 v64, v0
	v_mov_b32_e32 v65, v0
	v_mov_b32_e32 v66, v0
	v_mov_b32_e32 v67, v0
	v_mov_b32_e32 v68, v0
	v_mov_b32_e32 v69, v0
	v_mov_b32_e32 v70, v0
	v_mov_b32_e32 v71, v0
	v_mov_b32_e32 v80, v0
	v_mov_b32_e32 v81, v0
	v_mov_b32_e32 v82, v0
	v_mov_b32_e32 v83, v0
	v_mov_b32_e32 v84, v0
	v_mov_b32_e32 v85, v0
	v_mov_b32_e32 v86, v0
	v_mov_b32_e32 v87, v0
	v_mov_b32_e32 v96, v0
	v_mov_b32_e32 v97, v0
	v_mov_b32_e32 v98, v0
	v_mov_b32_e32 v99, v0
	v_mov_b32_e32 v100, v0
	v_mov_b32_e32 v101, v0
	v_mov_b32_e32 v102, v0
	v_mov_b32_e32 v103, v0
	v_mov_b32_e32 v112, v0
	v_mov_b32_e32 v113, v0
	v_mov_b32_e32 v114, v0
	v_mov_b32_e32 v115, v0
	v_mov_b32_e32 v116, v0
	v_mov_b32_e32 v117, v0
	v_mov_b32_e32 v118, v0
	v_mov_b32_e32 v119, v0
	v_mov_b32_e32 v72, v0
	v_mov_b32_e32 v73, v0
	v_mov_b32_e32 v74, v0
	v_mov_b32_e32 v75, v0
	v_mov_b32_e32 v76, v0
	v_mov_b32_e32 v77, v0
	v_mov_b32_e32 v78, v0
	v_mov_b32_e32 v79, v0
	v_mov_b32_e32 v88, v0
	v_mov_b32_e32 v89, v0
	v_mov_b32_e32 v90, v0
	v_mov_b32_e32 v91, v0
	v_mov_b32_e32 v92, v0
	v_mov_b32_e32 v93, v0
	v_mov_b32_e32 v94, v0
	v_mov_b32_e32 v95, v0
	v_mov_b32_e32 v104, v0
	v_mov_b32_e32 v105, v0
	v_mov_b32_e32 v106, v0
	v_mov_b32_e32 v107, v0
	v_mov_b32_e32 v108, v0
	v_mov_b32_e32 v109, v0
	v_mov_b32_e32 v110, v0
	v_mov_b32_e32 v111, v0
	v_mov_b32_e32 v120, v0
	v_mov_b32_e32 v121, v0
	v_mov_b32_e32 v122, v0
	v_mov_b32_e32 v123, v0
	v_mov_b32_e32 v124, v0
	v_mov_b32_e32 v125, v0
	v_mov_b32_e32 v126, v0
	v_mov_b32_e32 v127, v0
	.p2align 6
